# v1 + GEMM2 K loop: double-buffered fragment sets, reads one MFMA block ahead, barrier between blocks
# baseline (speedup 1.0000x reference)
.LBB0_392:
	s_or_b64 exec, exec, s[16:17]
	s_ashr_i32 s18, s72, 5
	s_and_b32 s0, s67, 31
	s_ashr_i32 s19, s18, 31
	s_lshl_b32 s60, s0, 19
	s_lshl_b64 s[26:27], s[18:19], 18
	s_add_u32 s28, s2, s26
	s_addc_u32 s29, s3, s27
	s_lshl_b32 s0, s73, 19
	s_add_u32 s34, s5, s0
	s_addc_u32 s35, s33, 0
	s_cmp_lt_u32 s73, 16
	s_cselect_b64 s[16:17], -1, 0
	s_add_i32 s0, s73, -16
	s_lshr_b32 s0, s0, 2
	s_add_i32 s0, s0, 1
	s_cmp_gt_u32 s73, 15
	s_cselect_b32 s0, s0, 0
	s_lshl_b32 s19, s18, 7
	s_add_i32 s41, s0, s81
	s_or_b32 s40, s19, s37
	s_mul_hi_i32 s42, s41, 0x3000
	s_mulk_i32 s41, 0x3000
	s_add_u32 s43, s88, s41
	s_addc_u32 s44, s89, s42
	s_ashr_i32 s41, s40, 31
	s_lshl_b64 s[40:41], s[40:41], 2
	s_add_u32 s42, s43, s40
	s_addc_u32 s43, s44, s41
	v_mov_b32_e32 v139, v81
	v_lshl_add_u64 v[0:1], s[42:43], 0, v[138:139]
	s_mov_b64 s[42:43], 0x42000
	v_lshl_add_u64 v[2:3], v[0:1], 0, s[42:43]
	s_add_i32 s42, s36, s0
	s_ashr_i32 s43, s42, 31
	s_lshl_b64 s[42:43], s[42:43], 12
	s_add_u32 s0, s48, s42
	s_addc_u32 s42, s49, s43
	s_add_u32 s40, s0, s40
	s_mov_b32 s0, 0x42000
	s_addc_u32 s41, s42, s41
	v_add_co_u32_e32 v0, vcc, s0, v0
	v_lshl_add_u64 v[16:17], s[40:41], 0, v[138:139]
	s_nop 0
	v_addc_co_u32_e32 v1, vcc, 0, v1, vcc
	s_mov_b32 m0, s52
	s_waitcnt lgkmcnt(0)
	s_barrier
	flat_load_dwordx4 v[8:11], v[2:3] offset:16
	flat_load_dwordx4 v[4:7], v[16:17]
	flat_load_dwordx4 v[12:15], v[0:1]
	s_nop 0
	flat_load_dwordx4 v[0:3], v[16:17] offset:16
	v_lshl_add_u64 v[16:17], v[114:115], 1, s[28:29]
	global_load_lds_dwordx4 v[16:17], off
	v_lshl_add_u64 v[16:17], v[116:117], 1, s[28:29]
	s_mov_b32 m0, s63
	v_mov_b32_e32 v28, 0
	global_load_lds_dwordx4 v[16:17], off
	v_lshl_add_u64 v[16:17], v[118:119], 1, s[34:35]
	s_add_i32 m0, s50, 0x4000
	v_lshl_add_u64 v[82:83], v[128:129], 0, s[60:61]
	global_load_lds_dwordx4 v[16:17], off
	v_lshl_add_u64 v[16:17], v[120:121], 1, s[34:35]
	s_mov_b32 m0, s64
	v_lshl_add_u64 v[84:85], v[130:131], 0, s[60:61]
	global_load_lds_dwordx4 v[16:17], off
	v_lshl_add_u64 v[16:17], v[122:123], 1, s[34:35]
	s_mov_b32 m0, s65
	v_lshl_add_u64 v[86:87], v[132:133], 0, s[60:61]
	global_load_lds_dwordx4 v[16:17], off
	v_lshl_add_u64 v[16:17], v[124:125], 1, s[34:35]
	s_mov_b32 m0, s66
	v_lshl_add_u64 v[88:89], v[134:135], 0, s[60:61]
	global_load_lds_dwordx4 v[16:17], off
	s_waitcnt vmcnt(0)
	s_mov_b32 s28, 0
	v_lshl_add_u64 v[90:91], v[126:127], 0, s[26:27]
	v_lshl_add_u64 v[92:93], v[136:137], 0, s[26:27]
	s_mov_b64 s[26:27], 0
	v_mov_b32_e32 v29, v28
	v_mov_b32_e32 v30, v28
	v_mov_b32_e32 v31, v28
	v_mov_b32_e32 v36, v28
	v_mov_b32_e32 v37, v28
	v_mov_b32_e32 v38, v28
	v_mov_b32_e32 v39, v28
	v_mov_b32_e32 v16, v28
	v_mov_b32_e32 v17, v28
	v_mov_b32_e32 v18, v28
	v_mov_b32_e32 v19, v28
	v_mov_b32_e32 v20, v28
	v_mov_b32_e32 v21, v28
	v_mov_b32_e32 v22, v28
	v_mov_b32_e32 v23, v28
	v_mov_b32_e32 v24, v28
	v_mov_b32_e32 v25, v28
	v_mov_b32_e32 v26, v28
	v_mov_b32_e32 v27, v28
	v_mov_b32_e32 v32, v28
	v_mov_b32_e32 v33, v28
	v_mov_b32_e32 v34, v28
	v_mov_b32_e32 v35, v28
	v_mov_b32_e32 v40, v28
	v_mov_b32_e32 v41, v28
	v_mov_b32_e32 v42, v28
	v_mov_b32_e32 v43, v28
	v_mov_b32_e32 v44, v28
	v_mov_b32_e32 v45, v28
	v_mov_b32_e32 v46, v28
	v_mov_b32_e32 v47, v28
	v_mov_b32_e32 v48, v28
	v_mov_b32_e32 v49, v28
	v_mov_b32_e32 v50, v28
	v_mov_b32_e32 v51, v28
	v_mov_b32_e32 v52, v28
	v_mov_b32_e32 v53, v28
	v_mov_b32_e32 v54, v28
	v_mov_b32_e32 v55, v28
	v_mov_b32_e32 v56, v28
	v_mov_b32_e32 v57, v28
	v_mov_b32_e32 v58, v28
	v_mov_b32_e32 v59, v28
	v_mov_b32_e32 v60, v28
	v_mov_b32_e32 v61, v28
	v_mov_b32_e32 v62, v28
	v_mov_b32_e32 v63, v28
	v_mov_b32_e32 v64, v28
	v_mov_b32_e32 v65, v28
	v_mov_b32_e32 v66, v28
	v_mov_b32_e32 v67, v28
	v_mov_b32_e32 v68, v28
	v_mov_b32_e32 v69, v28
	v_mov_b32_e32 v70, v28
	v_mov_b32_e32 v71, v28
	v_mov_b32_e32 v72, v28
	v_mov_b32_e32 v73, v28
	v_mov_b32_e32 v74, v28
	v_mov_b32_e32 v75, v28
	v_mov_b32_e32 v76, v28
	v_mov_b32_e32 v77, v28
	v_mov_b32_e32 v78, v28
	v_mov_b32_e32 v79, v28
	s_waitcnt vmcnt(0) lgkmcnt(0)
	s_barrier
	v_add_u32_e32 v248, v153, v151
	v_add_u32_e32 v249, v153, v152
	v_add_u32_e32 v202, v154, v151
	v_add_u32_e32 v203, v154, v152
	ds_read_b128 v[190:193], v248
	ds_read_b128 v[212:215], v202 offset:16384
	ds_read_b128 v[224:227], v202 offset:18432
	ds_read_b128 v[228:231], v202 offset:20480
	ds_read_b128 v[170:173], v202 offset:22528
	ds_read_b128 v[194:197], v248 offset:2048
	ds_read_b128 v[198:201], v248 offset:4096
	ds_read_b128 v[208:211], v248 offset:6144
.LBB0_393:
	s_and_b32 s0, s28, 1
	s_xor_b32 s29, s0, 1
	s_mul_i32 s29, s29, 0xc000
	s_mov_b32 s100, s29
	s_add_i32 s34, s52, s29
	v_lshl_add_u64 v[174:175], v[92:93], 0, s[26:27]
	s_mul_i32 s0, s0, 0xc000
	s_add_i32 s29, s50, s29
	s_mov_b32 m0, s34
	v_lshl_add_u64 v[176:177], v[88:89], 0, s[26:27]
	s_add_i32 s0, s0, 0
	global_load_lds_dwordx4 v[174:175], off
	s_add_i32 m0, s29, 0x4000
	v_lshl_add_u64 v[178:179], v[86:87], 0, s[26:27]
	v_add_u32_e32 v80, s0, v249
	v_add_u32_e32 v139, s0, v203
	global_load_lds_dwordx4 v[176:177], off
	s_add_i32 m0, s29, 0x4400
	v_lshl_add_u64 v[140:141], v[90:91], 0, s[26:27]
	v_lshl_add_u64 v[142:143], v[82:83], 0, s[26:27]
	global_load_lds_dwordx4 v[178:179], off
	v_lshl_add_u64 v[144:145], v[84:85], 0, s[26:27]
	s_add_i32 s0, s29, 0x4800
	s_add_i32 m0, s34, 0x400
	s_addk_i32 s29, 0x4c00
	s_waitcnt lgkmcnt(0)
	ds_read_b128 v[232:235], v80
	ds_read_b128 v[94:97], v139 offset:16384
	ds_read_b128 v[98:101], v139 offset:18432
	ds_read_b128 v[102:105], v139 offset:20480
	ds_read_b128 v[106:109], v139 offset:22528
	ds_read_b128 v[236:239], v80 offset:2048
	ds_read_b128 v[240:243], v80 offset:4096
	ds_read_b128 v[244:247], v80 offset:6144
	v_mfma_f32_16x16x32_bf16 v[76:79], v[190:193], v[212:215], v[76:79]
	v_mfma_f32_16x16x32_bf16 v[72:75], v[190:193], v[224:227], v[72:75]
	v_mfma_f32_16x16x32_bf16 v[68:71], v[190:193], v[228:231], v[68:71]
	v_mfma_f32_16x16x32_bf16 v[64:67], v[190:193], v[170:173], v[64:67]
	global_load_lds_dwordx4 v[140:141], off
	s_mov_b32 m0, s0
	v_mfma_f32_16x16x32_bf16 v[60:63], v[194:197], v[212:215], v[60:63]
	v_mfma_f32_16x16x32_bf16 v[56:59], v[194:197], v[224:227], v[56:59]
	global_load_lds_dwordx4 v[142:143], off
	s_mov_b32 m0, s29
	v_mfma_f32_16x16x32_bf16 v[52:55], v[194:197], v[228:231], v[52:55]
	v_mfma_f32_16x16x32_bf16 v[48:51], v[194:197], v[170:173], v[48:51]
	global_load_lds_dwordx4 v[144:145], off
	v_mfma_f32_16x16x32_bf16 v[44:47], v[198:201], v[212:215], v[44:47]
	v_mfma_f32_16x16x32_bf16 v[40:43], v[198:201], v[224:227], v[40:43]
	v_mfma_f32_16x16x32_bf16 v[32:35], v[198:201], v[228:231], v[32:35]
	v_mfma_f32_16x16x32_bf16 v[24:27], v[198:201], v[170:173], v[24:27]
	v_mfma_f32_16x16x32_bf16 v[20:23], v[208:211], v[212:215], v[20:23]
	v_mfma_f32_16x16x32_bf16 v[16:19], v[208:211], v[224:227], v[16:19]
	v_mfma_f32_16x16x32_bf16 v[36:39], v[208:211], v[228:231], v[36:39]
	v_mfma_f32_16x16x32_bf16 v[28:31], v[208:211], v[170:173], v[28:31]
	s_add_i32 s28, s28, 1
	s_add_u32 s26, s26, 0x80
	s_addc_u32 s27, s27, 0
	s_waitcnt vmcnt(0)
	s_waitcnt vmcnt(0) lgkmcnt(0)
	s_barrier
	v_add_u32_e32 v146, s100, v248
	v_add_u32_e32 v110, s100, v202
	ds_read_b128 v[190:193], v146
	ds_read_b128 v[212:215], v110 offset:16384
	ds_read_b128 v[224:227], v110 offset:18432
	ds_read_b128 v[228:231], v110 offset:20480
	ds_read_b128 v[170:173], v110 offset:22528
	ds_read_b128 v[194:197], v146 offset:2048
	ds_read_b128 v[198:201], v146 offset:4096
	ds_read_b128 v[208:211], v146 offset:6144
	v_mfma_f32_16x16x32_bf16 v[76:79], v[232:235], v[94:97], v[76:79]
	v_mfma_f32_16x16x32_bf16 v[72:75], v[232:235], v[98:101], v[72:75]
	v_mfma_f32_16x16x32_bf16 v[68:71], v[232:235], v[102:105], v[68:71]
	v_mfma_f32_16x16x32_bf16 v[64:67], v[232:235], v[106:109], v[64:67]
	v_mfma_f32_16x16x32_bf16 v[60:63], v[236:239], v[94:97], v[60:63]
	v_mfma_f32_16x16x32_bf16 v[56:59], v[236:239], v[98:101], v[56:59]
	v_mfma_f32_16x16x32_bf16 v[52:55], v[236:239], v[102:105], v[52:55]
	v_mfma_f32_16x16x32_bf16 v[48:51], v[236:239], v[106:109], v[48:51]
	v_mfma_f32_16x16x32_bf16 v[44:47], v[240:243], v[94:97], v[44:47]
	v_mfma_f32_16x16x32_bf16 v[40:43], v[240:243], v[98:101], v[40:43]
	v_mfma_f32_16x16x32_bf16 v[32:35], v[240:243], v[102:105], v[32:35]
	v_mfma_f32_16x16x32_bf16 v[24:27], v[240:243], v[106:109], v[24:27]
	v_mfma_f32_16x16x32_bf16 v[20:23], v[244:247], v[94:97], v[20:23]
	v_mfma_f32_16x16x32_bf16 v[16:19], v[244:247], v[98:101], v[16:19]
	v_mfma_f32_16x16x32_bf16 v[36:39], v[244:247], v[102:105], v[36:39]
	v_mfma_f32_16x16x32_bf16 v[28:31], v[244:247], v[106:109], v[28:31]
	s_cmpk_eq_i32 s26, 0x780
	s_cbranch_scc0 .LBB0_393
	v_add_u32_e32 v80, v155, v151
	ds_read_b128 v[82:85], v80 offset:49152
	v_add_u32_e32 v110, v156, v151
	ds_read_b128 v[86:89], v110 offset:16384
	ds_read_b128 v[90:93], v80 offset:51200
	ds_read_b128 v[94:97], v110 offset:18432
	ds_read_b128 v[98:101], v80 offset:53248
	ds_read_b128 v[102:105], v110 offset:20480
	ds_read_b128 v[106:109], v80 offset:55296
	ds_read_b128 v[110:113], v110 offset:22528
	s_waitcnt lgkmcnt(5)
	v_mfma_f32_16x16x32_bf16 v[60:63], v[90:93], v[86:89], v[60:63]
	s_or_b32 s26, s19, s54
	s_lshl_b32 s0, s73, 8
	s_ashr_i32 s27, s26, 31
	s_waitcnt lgkmcnt(3)
	v_mfma_f32_16x16x32_bf16 v[44:47], v[98:101], v[86:89], v[44:47]
	v_mov_b32_e32 v139, v188
	s_add_i32 s28, s0, s51
	s_lshl_b64 s[34:35], s[26:27], 1
	v_mfma_f32_16x16x32_bf16 v[76:79], v[82:85], v[86:89], v[76:79]
	s_add_u32 s40, s55, s34
	s_addc_u32 s41, s56, s35
	s_ashr_i32 s29, s28, 31
	s_waitcnt lgkmcnt(1)
	v_mfma_f32_16x16x32_bf16 v[86:89], v[106:109], v[86:89], v[20:23]
	s_and_b64 vcc, exec, s[8:9]
	s_nop 1
	v_add_u32_e32 v20, v155, v152
	v_mfma_f32_16x16x32_bf16 v[144:147], v[106:109], v[94:97], v[16:19]
	v_add_u32_e32 v21, v156, v152
	s_nop 1
	ds_read_b128 v[16:19], v20 offset:49152
	v_mfma_f32_16x16x32_bf16 v[72:75], v[82:85], v[94:97], v[72:75]
	v_mfma_f32_16x16x32_bf16 v[140:143], v[82:85], v[102:105], v[68:71]
	s_waitcnt lgkmcnt(1)
	v_mfma_f32_16x16x32_bf16 v[82:85], v[82:85], v[110:113], v[64:67]
	v_mfma_f32_16x16x32_bf16 v[56:59], v[90:93], v[94:97], v[56:59]
	v_mfma_f32_16x16x32_bf16 v[52:55], v[90:93], v[102:105], v[52:55]
	v_mfma_f32_16x16x32_bf16 v[48:51], v[90:93], v[110:113], v[48:51]
	v_mfma_f32_16x16x32_bf16 v[40:43], v[98:101], v[94:97], v[40:43]
	v_mfma_f32_16x16x32_bf16 v[32:35], v[98:101], v[102:105], v[32:35]
	v_mfma_f32_16x16x32_bf16 v[98:101], v[98:101], v[110:113], v[24:27]
	v_mfma_f32_16x16x32_bf16 v[36:39], v[106:109], v[102:105], v[36:39]
	v_mfma_f32_16x16x32_bf16 v[102:105], v[106:109], v[110:113], v[28:31]
	ds_read_b128 v[94:97], v21 offset:16384
	ds_read_b128 v[24:27], v20 offset:51200
	ds_read_b128 v[106:109], v21 offset:18432
	ds_read_b128 v[110:113], v20 offset:53248
	ds_read_b128 v[158:161], v21 offset:20480
	ds_read_b128 v[162:165], v20 offset:55296
	ds_read_b128 v[166:169], v21 offset:22528
	s_waitcnt vmcnt(0)
	s_waitcnt lgkmcnt(0)
	v_mfma_f32_16x16x32_bf16 v[68:71], v[16:19], v[94:97], v[76:79]
	s_barrier
	v_mfma_f32_16x16x32_bf16 v[64:67], v[16:19], v[106:109], v[72:75]
	v_mfma_f32_16x16x32_bf16 v[20:23], v[16:19], v[158:161], v[140:143]
	v_mfma_f32_16x16x32_bf16 v[16:19], v[16:19], v[166:169], v[82:85]
	s_nop 1
	v_ashrrev_i32_e32 v140, 3, v139
	v_ashrrev_i32_e32 v141, 31, v140
	v_mfma_f32_16x16x32_bf16 v[76:79], v[24:27], v[94:97], v[60:63]
	v_mfma_f32_16x16x32_bf16 v[72:75], v[24:27], v[106:109], v[56:59]
	v_mfma_f32_16x16x32_bf16 v[28:31], v[24:27], v[158:161], v[52:55]
	v_mfma_f32_16x16x32_bf16 v[24:27], v[24:27], v[166:169], v[48:51]
	v_mfma_f32_16x16x32_bf16 v[90:93], v[110:113], v[94:97], v[44:47]
	v_mfma_f32_16x16x32_bf16 v[82:85], v[110:113], v[106:109], v[40:43]
	v_mfma_f32_16x16x32_bf16 v[40:43], v[110:113], v[158:161], v[32:35]
	v_mfma_f32_16x16x32_bf16 v[32:35], v[110:113], v[166:169], v[98:101]
	v_mfma_f32_16x16x32_bf16 v[94:97], v[162:165], v[94:97], v[86:89]
	v_mfma_f32_16x16x32_bf16 v[86:89], v[162:165], v[106:109], v[144:147]
	v_mfma_f32_16x16x32_bf16 v[44:47], v[162:165], v[158:161], v[36:39]
	v_and_b32_e32 v159, 7, v139
	v_lshlrev_b32_e32 v80, 4, v159
	v_lshl_add_u64 v[142:143], s[40:41], 0, v[80:81]
	v_mfma_f32_16x16x32_bf16 v[36:39], v[162:165], v[166:169], v[102:105]
	s_lshl_b64 s[40:41], s[28:29], 11
	v_lshl_add_u64 v[144:145], v[142:143], 0, s[40:41]
	s_mov_b64 s[40:41], -1
	s_cbranch_vccz .LBB0_396
	v_lshlrev_b64 v[146:147], 11, v[140:141]
	v_lshl_add_u64 v[60:61], v[144:145], 0, v[146:147]
	s_movk_i32 s0, 0x4000
	v_add_co_u32_e32 v52, vcc, s0, v60
	s_mov_b32 s0, 0x8000
	s_nop 0
	v_addc_co_u32_e32 v53, vcc, 0, v61, vcc
	v_add_co_u32_e32 v56, vcc, s0, v60
	s_mov_b32 s0, 0xc000
	s_nop 0
	v_addc_co_u32_e32 v57, vcc, 0, v61, vcc
	flat_load_dwordx4 v[48:51], v[60:61]
	v_add_co_u32_e32 v60, vcc, s0, v60
	flat_load_dwordx4 v[52:55], v[52:53]
	s_nop 0
	v_addc_co_u32_e32 v61, vcc, 0, v61, vcc
	flat_load_dwordx4 v[56:59], v[56:57]
	s_mov_b64 s[40:41], 0
	flat_load_dwordx4 v[160:163], v[60:61]
	s_waitcnt vmcnt(0) lgkmcnt(0)
	v_lshlrev_b32_e32 v110, 16, v48
	v_and_b32_e32 v111, 0xffff0000, v48
	v_lshlrev_b32_e32 v112, 16, v49
	v_and_b32_e32 v113, 0xffff0000, v49
	v_lshlrev_b32_e32 v106, 16, v50
	v_and_b32_e32 v107, 0xffff0000, v50
	v_lshlrev_b32_e32 v108, 16, v51
	v_and_b32_e32 v109, 0xffff0000, v51
	v_lshlrev_b32_e32 v102, 16, v52
	v_and_b32_e32 v103, 0xffff0000, v52
	v_lshlrev_b32_e32 v104, 16, v53
	v_and_b32_e32 v105, 0xffff0000, v53
	v_lshlrev_b32_e32 v98, 16, v54
	v_and_b32_e32 v99, 0xffff0000, v54
	v_lshlrev_b32_e32 v100, 16, v55
	v_and_b32_e32 v101, 0xffff0000, v55
	v_lshlrev_b32_e32 v60, 16, v56
	v_and_b32_e32 v61, 0xffff0000, v56
	v_lshlrev_b32_e32 v62, 16, v57
	v_and_b32_e32 v63, 0xffff0000, v57
	v_lshlrev_b32_e32 v56, 16, v58
	v_and_b32_e32 v57, 0xffff0000, v58
	v_lshlrev_b32_e32 v58, 16, v59
	v_and_b32_e32 v59, 0xffff0000, v59
	v_lshlrev_b32_e32 v52, 16, v160
	v_and_b32_e32 v53, 0xffff0000, v160
	v_lshlrev_b32_e32 v54, 16, v161
	v_and_b32_e32 v55, 0xffff0000, v161
	v_lshlrev_b32_e32 v48, 16, v162
	v_and_b32_e32 v49, 0xffff0000, v162
	v_lshlrev_b32_e32 v50, 16, v163
	v_and_b32_e32 v51, 0xffff0000, v163

	.amdhsa_kernel _ZN2mk4megaENS_6ParamsE
		.amdhsa_group_segment_fixed_size 0
		.amdhsa_private_segment_fixed_size 0
		.amdhsa_kernarg_size 464
		.amdhsa_user_sgpr_count 2
		.amdhsa_user_sgpr_dispatch_ptr 0
		.amdhsa_user_sgpr_queue_ptr 0
		.amdhsa_user_sgpr_kernarg_segment_ptr 1
		.amdhsa_user_sgpr_dispatch_id 0
		.amdhsa_user_sgpr_kernarg_preload_length 0
		.amdhsa_user_sgpr_kernarg_preload_offset 0
		.amdhsa_user_sgpr_private_segment_size 0
		.amdhsa_uses_dynamic_stack 0
		.amdhsa_enable_private_segment 0
		.amdhsa_system_sgpr_workgroup_id_x 1
		.amdhsa_system_sgpr_workgroup_id_y 0
		.amdhsa_system_sgpr_workgroup_id_z 0
		.amdhsa_system_sgpr_workgroup_info 0
		.amdhsa_system_vgpr_workitem_id 0
		.amdhsa_next_free_vgpr 256
		.amdhsa_next_free_sgpr 102
		.amdhsa_accum_offset 256
		.amdhsa_reserve_vcc 1
		.amdhsa_float_round_mode_32 0
		.amdhsa_float_round_mode_16_64 0
		.amdhsa_float_denorm_mode_32 3
		.amdhsa_float_denorm_mode_16_64 3
		.amdhsa_dx10_clamp 1
		.amdhsa_ieee_mode 1
		.amdhsa_fp16_overflow 0
		.amdhsa_tg_split 0
		.amdhsa_exception_fp_ieee_invalid_op 0
		.amdhsa_exception_fp_denorm_src 0
		.amdhsa_exception_fp_ieee_div_zero 0
		.amdhsa_exception_fp_ieee_overflow 0
		.amdhsa_exception_fp_ieee_underflow 0
		.amdhsa_exception_fp_ieee_inexact 0
		.amdhsa_exception_int_div_zero 0
	.end_amdhsa_kernel

amdhsa.kernels:
  - .agpr_count:     0
    .args:
      - .offset:         0
        .size:           208
        .value_kind:     by_value
      - .offset:         208
        .size:           4
        .value_kind:     hidden_block_count_x
      - .offset:         212
        .size:           4
        .value_kind:     hidden_block_count_y
      - .offset:         216
        .size:           4
        .value_kind:     hidden_block_count_z
      - .offset:         220
        .size:           2
        .value_kind:     hidden_group_size_x
      - .offset:         222
        .size:           2
        .value_kind:     hidden_group_size_y
      - .offset:         224
        .size:           2
        .value_kind:     hidden_group_size_z
      - .offset:         226
        .size:           2
        .value_kind:     hidden_remainder_x
      - .offset:         228
        .size:           2
        .value_kind:     hidden_remainder_y
      - .offset:         230
        .size:           2
        .value_kind:     hidden_remainder_z
      - .offset:         248
        .size:           8
        .value_kind:     hidden_global_offset_x
      - .offset:         256
        .size:           8
        .value_kind:     hidden_global_offset_y
      - .offset:         264
        .size:           8
        .value_kind:     hidden_global_offset_z
      - .offset:         272
        .size:           2
        .value_kind:     hidden_grid_dims
      - .offset:         328
        .size:           4
        .value_kind:     hidden_dynamic_lds_size
    .group_segment_fixed_size: 0
    .kernarg_segment_align: 8
    .kernarg_segment_size: 464
    .language:       OpenCL C
    .language_version:
      - 2
      - 0
    .max_flat_workgroup_size: 512
    .name:           _ZN2mk4megaENS_6ParamsE
    .private_segment_fixed_size: 0
    .sgpr_count:     108
    .sgpr_spill_count: 305
    .symbol:         _ZN2mk4megaENS_6ParamsE.kd
    .uniform_work_group_size: 1
    .uses_dynamic_stack: false
    .vgpr_count:     256
    .vgpr_spill_count: 0
    .wavefront_size: 64
